# P11 fixed passes: pipelined K/V fragment reads (ring buffers) + s_setprio 1 around MFMA segments
# speedup vs baseline: 1.0090x; 1.0053x over previous
.Lst1_a:
.LBB0_1233:
	s_waitcnt vmcnt(6)
	s_waitcnt lgkmcnt(0)
	s_barrier
	v_lshl_add_u32 v254, s4, 14, v217
	v_add_u32_e32 v255, v254, v225
	ds_read_b128 v[228:231], v255
	ds_read_b128 v[232:235], v255 offset:8192
	v_add_u32_e32 v255, v254, v224
	ds_read_b128 v[236:239], v255
	ds_read_b128 v[240:243], v255 offset:8192
	s_add_i32 s5, s4, 1
	s_cmp_lg_u32 s4, 2
	s_setprio 1
	s_waitcnt lgkmcnt(2)
	v_add_u32_e32 v255, v254, v223
	ds_read_b128 v[246:249], v255
	ds_read_b128 v[250:253], v255 offset:8192
	v_mfma_f32_32x32x16_bf16 v[130:145], v[232:235], v[190:193], 0
	v_mfma_f32_32x32x16_bf16 v[146:161], v[228:231], v[190:193], 0
	s_waitcnt lgkmcnt(2)
	v_add_u32_e32 v255, v254, v222
	ds_read_b128 v[228:231], v255
	ds_read_b128 v[232:235], v255 offset:8192
	v_mfma_f32_32x32x16_bf16 v[130:145], v[240:243], v[186:189], v[130:145]
	v_mfma_f32_32x32x16_bf16 v[146:161], v[236:239], v[186:189], v[146:161]
	s_waitcnt lgkmcnt(2)
	v_add_u32_e32 v255, v254, v221
	ds_read_b128 v[236:239], v255
	ds_read_b128 v[240:243], v255 offset:8192
	v_mfma_f32_32x32x16_bf16 v[130:145], v[250:253], v[182:185], v[130:145]
	v_mfma_f32_32x32x16_bf16 v[146:161], v[246:249], v[182:185], v[146:161]
	s_waitcnt lgkmcnt(2)
	v_add_u32_e32 v255, v254, v220
	ds_read_b128 v[246:249], v255
	ds_read_b128 v[250:253], v255 offset:8192
	v_mfma_f32_32x32x16_bf16 v[130:145], v[232:235], v[178:181], v[130:145]
	v_mfma_f32_32x32x16_bf16 v[146:161], v[228:231], v[178:181], v[146:161]
	s_waitcnt lgkmcnt(2)
	v_add_u32_e32 v255, v254, v219
	ds_read_b128 v[228:231], v255
	ds_read_b128 v[232:235], v255 offset:8192
	v_mfma_f32_32x32x16_bf16 v[130:145], v[240:243], v[174:177], v[130:145]
	v_mfma_f32_32x32x16_bf16 v[146:161], v[236:239], v[174:177], v[146:161]
	s_waitcnt lgkmcnt(2)
	v_add_u32_e32 v255, v254, v218
	ds_read_b128 v[236:239], v255
	ds_read_b128 v[240:243], v255 offset:8192
	v_mfma_f32_32x32x16_bf16 v[130:145], v[250:253], v[170:173], v[130:145]
	v_mfma_f32_32x32x16_bf16 v[146:161], v[246:249], v[170:173], v[146:161]
	s_waitcnt lgkmcnt(2)
	v_mfma_f32_32x32x16_bf16 v[130:145], v[232:235], v[166:169], v[130:145]
	v_mfma_f32_32x32x16_bf16 v[146:161], v[228:231], v[166:169], v[146:161]
	s_waitcnt lgkmcnt(0)
	v_mfma_f32_32x32x16_bf16 v[130:145], v[240:243], v[162:165], v[130:145]
	v_mfma_f32_32x32x16_bf16 v[146:161], v[236:239], v[162:165], v[146:161]
	s_setprio 0
	s_nop 10
	v_fmamk_f32 v138, v138, 0x3e0293ee, v215
	v_fmamk_f32 v139, v139, 0x3e0293ee, v215
	v_fmamk_f32 v140, v140, 0x3e0293ee, v215
	v_fmamk_f32 v141, v141, 0x3e0293ee, v215
	v_fmamk_f32 v142, v142, 0x3e0293ee, v215
	v_exp_f32_e32 v226, v138
	v_fmamk_f32 v130, v130, 0x3e0293ee, v215
	v_fmamk_f32 v138, v155, 0x3e0293ee, v215
	v_exp_f32_e32 v155, v139
	v_fmamk_f32 v139, v156, 0x3e0293ee, v215
	v_exp_f32_e32 v156, v140
	v_fmamk_f32 v140, v157, 0x3e0293ee, v215
	v_exp_f32_e32 v157, v141
	v_fmamk_f32 v141, v158, 0x3e0293ee, v215
	v_exp_f32_e32 v158, v142
	v_fmamk_f32 v142, v159, 0x3e0293ee, v215
	v_fmamk_f32 v146, v146, 0x3e0293ee, v215
	v_exp_f32_e32 v159, v142
	v_fmamk_f32 v142, v143, 0x3e0293ee, v215
	v_exp_f32_e32 v146, v146
	v_fmamk_f32 v147, v147, 0x3e0293ee, v215
	v_exp_f32_e32 v227, v142
	v_fmamk_f32 v142, v160, 0x3e0293ee, v215
	v_exp_f32_e32 v147, v147
	v_fmamk_f32 v148, v148, 0x3e0293ee, v215
	v_exp_f32_e32 v160, v142
	v_fmamk_f32 v142, v144, 0x3e0293ee, v215
	v_exp_f32_e32 v148, v148
	v_fmamk_f32 v149, v149, 0x3e0293ee, v215
	v_exp_f32_e32 v228, v142
	v_fmamk_f32 v142, v161, 0x3e0293ee, v215
	v_exp_f32_e32 v149, v149
	v_fmamk_f32 v150, v150, 0x3e0293ee, v215
	v_exp_f32_e32 v161, v142
	v_fmamk_f32 v142, v145, 0x3e0293ee, v215
	v_exp_f32_e32 v150, v150
	v_fmamk_f32 v151, v151, 0x3e0293ee, v215
	v_exp_f32_e32 v229, v142
	v_add_f32_e32 v142, 0, v146
	v_exp_f32_e32 v151, v151
	v_fmamk_f32 v152, v152, 0x3e0293ee, v215
	v_add_f32_e32 v142, v147, v142
	v_exp_f32_e32 v152, v152
	v_fmamk_f32 v153, v153, 0x3e0293ee, v215
	v_add_f32_e32 v142, v148, v142
	v_exp_f32_e32 v153, v153
	v_fmamk_f32 v154, v154, 0x3e0293ee, v215
	v_add_f32_e32 v142, v149, v142
	v_exp_f32_e32 v154, v154
	v_add_f32_e32 v142, v150, v142
	v_exp_f32_e32 v138, v138
	v_add_f32_e32 v142, v151, v142
	v_exp_f32_e32 v139, v139
	v_add_f32_e32 v142, v152, v142
	v_exp_f32_e32 v140, v140
	v_add_f32_e32 v142, v153, v142
	v_exp_f32_e32 v141, v141
	v_add_f32_e32 v142, v154, v142
	v_add_f32_e32 v142, v138, v142
	v_add_f32_e32 v142, v139, v142
	v_add_f32_e32 v142, v140, v142
	v_exp_f32_e32 v130, v130
	v_fmamk_f32 v131, v131, 0x3e0293ee, v215
	v_add_f32_e32 v142, v141, v142
	v_exp_f32_e32 v131, v131
	v_fmamk_f32 v132, v132, 0x3e0293ee, v215
	v_add_f32_e32 v142, v159, v142
	v_exp_f32_e32 v132, v132
	v_fmamk_f32 v133, v133, 0x3e0293ee, v215
	v_add_f32_e32 v142, v160, v142
	v_exp_f32_e32 v133, v133
	v_fmamk_f32 v134, v134, 0x3e0293ee, v215
	v_add_f32_e32 v142, v161, v142
	v_exp_f32_e32 v134, v134
	v_fmamk_f32 v135, v135, 0x3e0293ee, v215
	v_add_f32_e32 v142, v130, v142
	v_exp_f32_e32 v135, v135
	v_fmamk_f32 v136, v136, 0x3e0293ee, v215
	v_add_f32_e32 v142, v131, v142
	v_exp_f32_e32 v136, v136
	v_fmamk_f32 v137, v137, 0x3e0293ee, v215
	v_add_f32_e32 v142, v132, v142
	v_exp_f32_e32 v137, v137
	v_add_f32_e32 v142, v133, v142
	v_add_f32_e32 v142, v134, v142
	v_add_f32_e32 v142, v135, v142
	v_add_f32_e32 v142, v136, v142
	v_add_f32_e32 v142, v137, v142
	v_add_f32_e32 v142, v226, v142
	v_add_f32_e32 v142, v155, v142
	v_add_f32_e32 v142, v156, v142
	v_add_f32_e32 v142, v157, v142
	v_add_f32_e32 v142, v158, v142
	v_add_f32_e32 v142, v227, v142
	v_add_f32_e32 v142, v228, v142
	v_add_f32_e32 v142, v229, v142
	v_mov_b32_e32 v143, v142
	s_nop 1
	v_permlane32_swap_b32_e32 v142, v143
	v_add_f32_e32 v142, v142, v143
	v_add_f32_e32 v211, v211, v142
	v_cvt_pk_bf16_f32 v142, v146, v147
	v_cvt_pk_bf16_f32 v143, v148, v149
	v_cvt_pk_bf16_f32 v144, v150, v151
	v_cvt_pk_bf16_f32 v145, v152, v153
	s_nop 0
	v_permlane32_swap_b32_e32 v142, v144
	v_permlane32_swap_b32_e32 v143, v145
	v_lshl_add_u32 v146, s4, 15, v216
	v_cvt_pk_bf16_f32 v138, v154, v138
	v_cvt_pk_bf16_f32 v139, v139, v140
	v_cvt_pk_bf16_f32 v140, v141, v159
	v_cvt_pk_bf16_f32 v141, v160, v161
	v_cvt_pk_bf16_f32 v130, v130, v131
	v_cvt_pk_bf16_f32 v131, v132, v133
	v_cvt_pk_bf16_f32 v132, v134, v135
	v_cvt_pk_bf16_f32 v133, v136, v137
	v_cvt_pk_bf16_f32 v134, v226, v155
	v_cvt_pk_bf16_f32 v135, v156, v157
	v_cvt_pk_bf16_f32 v136, v158, v227
	v_cvt_pk_bf16_f32 v137, v228, v229
	v_add_u32_e32 v152, 0xc000, v146
	s_waitcnt vmcnt(0)
	s_barrier
	s_add_i32 s98, s4, -1
	s_cmp_eq_u32 s4, 0
	s_cselect_b32 s98, 2, s98
	s_lshl_b32 s99, s98, 14
	s_add_i32 s99, s90, s99
	s_lshl_b32 s98, s98, 15
	s_add_i32 s98, s90, s98
	v_lshl_add_u64 v[236:237], v[194:195], 0, s[2:3]
	s_mov_b32 m0, s99
	s_nop 0
	global_load_lds_dwordx4 v[236:237], off
	v_lshl_add_u64 v[236:237], v[196:197], 0, s[2:3]
	s_add_i32 m0, s99, 0x2000
	s_nop 0
	global_load_lds_dwordx4 v[236:237], off
	v_lshl_add_u64 v[236:237], v[198:199], 0, s[2:3]
	s_add_i32 m0, s98, 0xc000
	s_nop 0
	global_load_lds_dwordx4 v[236:237], off
	v_lshl_add_u64 v[236:237], v[200:201], 0, s[2:3]
	s_add_i32 m0, s98, 0xe000
	s_nop 0
	global_load_lds_dwordx4 v[236:237], off
	v_lshl_add_u64 v[236:237], v[202:203], 0, s[2:3]
	s_add_i32 m0, s98, 0x10000
	s_nop 0
	global_load_lds_dwordx4 v[236:237], off
	v_lshl_add_u64 v[236:237], v[208:209], 0, s[2:3]
	s_add_i32 m0, s98, 0x12000
	s_nop 0
	global_load_lds_dwordx4 v[236:237], off
	s_cmp_lg_u32 s4, 2
	ds_read_b64_tr_b16 v[148:149], v146 offset:49152
	ds_read_b64_tr_b16 v[150:151], v146 offset:53248
	ds_read_b64_tr_b16 v[154:155], v146 offset:57344
	ds_read_b64_tr_b16 v[156:157], v146 offset:61440
	ds_read_b64_tr_b16 v[158:159], v152 offset:16384
	ds_read_b64_tr_b16 v[160:161], v152 offset:20480
	ds_read_b64_tr_b16 v[232:233], v152 offset:24576
	ds_read_b64_tr_b16 v[234:235], v152 offset:28672
	ds_read_b64_tr_b16 v[236:237], v146 offset:49664
	ds_read_b64_tr_b16 v[238:239], v146 offset:53760
	ds_read_b64_tr_b16 v[240:241], v146 offset:57856
	ds_read_b64_tr_b16 v[242:243], v146 offset:61952
	s_setprio 1
	s_waitcnt lgkmcnt(8)
	ds_read_b64_tr_b16 v[246:247], v152 offset:16896
	ds_read_b64_tr_b16 v[248:249], v152 offset:20992
	ds_read_b64_tr_b16 v[250:251], v152 offset:25088
	ds_read_b64_tr_b16 v[252:253], v152 offset:29184
	v_mfma_f32_32x32x16_bf16 v[114:129], v[142:145], v[148:151], v[114:129]
	v_permlane32_swap_b32_e32 v138, v140
	v_permlane32_swap_b32_e32 v139, v141
	v_permlane32_swap_b32_e32 v130, v132
	v_permlane32_swap_b32_e32 v131, v133
	v_mfma_f32_32x32x16_bf16 v[114:129], v[138:141], v[154:157], v[114:129]
	v_permlane32_swap_b32_e32 v134, v136
	v_permlane32_swap_b32_e32 v135, v137
	s_cselect_b32 s4, s5, 0
	s_add_u32 s2, s2, 0x100000
	s_addc_u32 s3, s3, 0
	s_waitcnt lgkmcnt(8)
	ds_read_b64_tr_b16 v[148:149], v146 offset:50176
	ds_read_b64_tr_b16 v[150:151], v146 offset:54272
	ds_read_b64_tr_b16 v[154:155], v146 offset:58368
	ds_read_b64_tr_b16 v[156:157], v146 offset:62464
	v_mfma_f32_32x32x16_bf16 v[114:129], v[130:133], v[158:161], v[114:129]
	v_mfma_f32_32x32x16_bf16 v[114:129], v[134:137], v[232:235], v[114:129]
	s_cmp_eq_u32 s2, 0x2200000
	s_waitcnt lgkmcnt(8)
	ds_read_b64_tr_b16 v[158:159], v152 offset:17408
	ds_read_b64_tr_b16 v[160:161], v152 offset:21504
	ds_read_b64_tr_b16 v[232:233], v152 offset:25600
	ds_read_b64_tr_b16 v[234:235], v152 offset:29696
	v_mfma_f32_32x32x16_bf16 v[98:113], v[142:145], v[236:239], v[98:113]
	v_mfma_f32_32x32x16_bf16 v[98:113], v[138:141], v[240:243], v[98:113]
	s_waitcnt lgkmcnt(8)
	ds_read_b64_tr_b16 v[236:237], v146 offset:50688
	ds_read_b64_tr_b16 v[238:239], v146 offset:54784
	ds_read_b64_tr_b16 v[240:241], v146 offset:58880
	ds_read_b64_tr_b16 v[242:243], v146 offset:62976
	v_mfma_f32_32x32x16_bf16 v[98:113], v[130:133], v[246:249], v[98:113]
	v_mfma_f32_32x32x16_bf16 v[98:113], v[134:137], v[250:253], v[98:113]
	s_waitcnt lgkmcnt(8)
	ds_read_b64_tr_b16 v[246:247], v152 offset:17920
	ds_read_b64_tr_b16 v[248:249], v152 offset:22016
	ds_read_b64_tr_b16 v[250:251], v152 offset:26112
	ds_read_b64_tr_b16 v[252:253], v152 offset:30208
	v_mfma_f32_32x32x16_bf16 v[82:97], v[142:145], v[148:151], v[82:97]
	v_mfma_f32_32x32x16_bf16 v[82:97], v[138:141], v[154:157], v[82:97]
	s_waitcnt lgkmcnt(8)
	ds_read_b64_tr_b16 v[148:149], v146 offset:51200
	ds_read_b64_tr_b16 v[150:151], v146 offset:55296
	ds_read_b64_tr_b16 v[154:155], v146 offset:59392
	ds_read_b64_tr_b16 v[156:157], v146 offset:63488
	v_mfma_f32_32x32x16_bf16 v[82:97], v[130:133], v[158:161], v[82:97]
	v_mfma_f32_32x32x16_bf16 v[82:97], v[134:137], v[232:235], v[82:97]
	s_waitcnt lgkmcnt(8)
	ds_read_b64_tr_b16 v[158:159], v152 offset:18432
	ds_read_b64_tr_b16 v[160:161], v152 offset:22528
	ds_read_b64_tr_b16 v[232:233], v152 offset:26624
	ds_read_b64_tr_b16 v[234:235], v152 offset:30720
	v_mfma_f32_32x32x16_bf16 v[66:81], v[142:145], v[236:239], v[66:81]
	v_mfma_f32_32x32x16_bf16 v[66:81], v[138:141], v[240:243], v[66:81]
	s_waitcnt lgkmcnt(8)
	ds_read_b64_tr_b16 v[236:237], v146 offset:51712
	ds_read_b64_tr_b16 v[238:239], v146 offset:55808
	ds_read_b64_tr_b16 v[240:241], v146 offset:59904
	ds_read_b64_tr_b16 v[242:243], v146 offset:64000
	v_mfma_f32_32x32x16_bf16 v[66:81], v[130:133], v[246:249], v[66:81]
	v_mfma_f32_32x32x16_bf16 v[66:81], v[134:137], v[250:253], v[66:81]
	s_waitcnt lgkmcnt(8)
	ds_read_b64_tr_b16 v[246:247], v152 offset:18944
	ds_read_b64_tr_b16 v[248:249], v152 offset:23040
	ds_read_b64_tr_b16 v[250:251], v152 offset:27136
	ds_read_b64_tr_b16 v[252:253], v152 offset:31232
	v_mfma_f32_32x32x16_bf16 v[50:65], v[142:145], v[148:151], v[50:65]
	v_mfma_f32_32x32x16_bf16 v[50:65], v[138:141], v[154:157], v[50:65]
	s_waitcnt lgkmcnt(8)
	ds_read_b64_tr_b16 v[148:149], v146 offset:52224
	ds_read_b64_tr_b16 v[150:151], v146 offset:56320
	ds_read_b64_tr_b16 v[154:155], v146 offset:60416
	ds_read_b64_tr_b16 v[156:157], v146 offset:64512
	v_mfma_f32_32x32x16_bf16 v[50:65], v[130:133], v[158:161], v[50:65]
	v_mfma_f32_32x32x16_bf16 v[50:65], v[134:137], v[232:235], v[50:65]
	s_waitcnt lgkmcnt(8)
	ds_read_b64_tr_b16 v[158:159], v152 offset:19456
	ds_read_b64_tr_b16 v[160:161], v152 offset:23552
	ds_read_b64_tr_b16 v[232:233], v152 offset:27648
	ds_read_b64_tr_b16 v[234:235], v152 offset:31744
	v_mfma_f32_32x32x16_bf16 v[34:49], v[142:145], v[236:239], v[34:49]
	v_mfma_f32_32x32x16_bf16 v[34:49], v[138:141], v[240:243], v[34:49]
	s_waitcnt lgkmcnt(8)
	ds_read_b64_tr_b16 v[236:237], v146 offset:52736
	ds_read_b64_tr_b16 v[238:239], v146 offset:56832
	ds_read_b64_tr_b16 v[240:241], v146 offset:60928
	ds_read_b64_tr_b16 v[242:243], v146 offset:65024
	v_mfma_f32_32x32x16_bf16 v[34:49], v[130:133], v[246:249], v[34:49]
	v_mfma_f32_32x32x16_bf16 v[34:49], v[134:137], v[250:253], v[34:49]
	s_waitcnt lgkmcnt(8)
	ds_read_b64_tr_b16 v[246:247], v152 offset:19968
	ds_read_b64_tr_b16 v[248:249], v152 offset:24064
	ds_read_b64_tr_b16 v[250:251], v152 offset:28160
	ds_read_b64_tr_b16 v[252:253], v152 offset:32256
	v_mfma_f32_32x32x16_bf16 v[18:33], v[142:145], v[148:151], v[18:33]
	v_mfma_f32_32x32x16_bf16 v[18:33], v[138:141], v[154:157], v[18:33]
	s_waitcnt lgkmcnt(8)
	v_mfma_f32_32x32x16_bf16 v[18:33], v[130:133], v[158:161], v[18:33]
	v_mfma_f32_32x32x16_bf16 v[18:33], v[134:137], v[232:235], v[18:33]
	s_waitcnt lgkmcnt(4)
	v_mfma_f32_32x32x16_bf16 v[2:17], v[142:145], v[236:239], v[2:17]
	v_mfma_f32_32x32x16_bf16 v[2:17], v[138:141], v[240:243], v[2:17]
	s_waitcnt lgkmcnt(0)
	v_mfma_f32_32x32x16_bf16 v[2:17], v[130:133], v[246:249], v[2:17]
	v_mfma_f32_32x32x16_bf16 v[2:17], v[134:137], v[250:253], v[2:17]
	s_setprio 0
	s_cbranch_scc0 .LBB0_1233
	s_cmp_ge_u32 s66, 0x80
	s_cbranch_scc1 .Lst1_b
	s_barrier

.Lst2_a:
.LBB0_1256:
	s_waitcnt vmcnt(6)
	s_waitcnt lgkmcnt(0)
	s_barrier
	v_lshl_add_u32 v254, s4, 14, v218
	v_add_u32_e32 v255, v254, v226
	ds_read_b128 v[228:231], v255
	ds_read_b128 v[232:235], v255 offset:8192
	v_add_u32_e32 v255, v254, v225
	ds_read_b128 v[236:239], v255
	ds_read_b128 v[240:243], v255 offset:8192
	s_add_i32 s5, s4, 1
	s_cmp_lg_u32 s4, 2
	s_setprio 1
	s_waitcnt lgkmcnt(2)
	v_add_u32_e32 v255, v254, v224
	ds_read_b128 v[246:249], v255
	ds_read_b128 v[250:253], v255 offset:8192
	v_mfma_f32_32x32x16_bf16 v[130:145], v[232:235], v[190:193], 0
	v_mfma_f32_32x32x16_bf16 v[146:161], v[228:231], v[190:193], 0
	s_waitcnt lgkmcnt(2)
	v_add_u32_e32 v255, v254, v223
	ds_read_b128 v[228:231], v255
	ds_read_b128 v[232:235], v255 offset:8192
	v_mfma_f32_32x32x16_bf16 v[130:145], v[240:243], v[186:189], v[130:145]
	v_mfma_f32_32x32x16_bf16 v[146:161], v[236:239], v[186:189], v[146:161]
	s_waitcnt lgkmcnt(2)
	v_add_u32_e32 v255, v254, v222
	ds_read_b128 v[236:239], v255
	ds_read_b128 v[240:243], v255 offset:8192
	v_mfma_f32_32x32x16_bf16 v[130:145], v[250:253], v[182:185], v[130:145]
	v_mfma_f32_32x32x16_bf16 v[146:161], v[246:249], v[182:185], v[146:161]
	s_waitcnt lgkmcnt(2)
	v_add_u32_e32 v255, v254, v221
	ds_read_b128 v[246:249], v255
	ds_read_b128 v[250:253], v255 offset:8192
	v_mfma_f32_32x32x16_bf16 v[130:145], v[232:235], v[178:181], v[130:145]
	v_mfma_f32_32x32x16_bf16 v[146:161], v[228:231], v[178:181], v[146:161]
	s_waitcnt lgkmcnt(2)
	v_add_u32_e32 v255, v254, v220
	ds_read_b128 v[228:231], v255
	ds_read_b128 v[232:235], v255 offset:8192
	v_mfma_f32_32x32x16_bf16 v[130:145], v[240:243], v[174:177], v[130:145]
	v_mfma_f32_32x32x16_bf16 v[146:161], v[236:239], v[174:177], v[146:161]
	s_waitcnt lgkmcnt(2)
	v_add_u32_e32 v255, v254, v219
	ds_read_b128 v[236:239], v255
	ds_read_b128 v[240:243], v255 offset:8192
	v_mfma_f32_32x32x16_bf16 v[130:145], v[250:253], v[170:173], v[130:145]
	v_mfma_f32_32x32x16_bf16 v[146:161], v[246:249], v[170:173], v[146:161]
	s_waitcnt lgkmcnt(2)
	v_mfma_f32_32x32x16_bf16 v[130:145], v[232:235], v[166:169], v[130:145]
	v_mfma_f32_32x32x16_bf16 v[146:161], v[228:231], v[166:169], v[146:161]
	s_waitcnt lgkmcnt(0)
	v_mfma_f32_32x32x16_bf16 v[130:145], v[240:243], v[162:165], v[130:145]
	v_mfma_f32_32x32x16_bf16 v[146:161], v[236:239], v[162:165], v[146:161]
	s_setprio 0
	s_nop 10
	v_fmamk_f32 v138, v138, 0x3e0293ee, v215
	v_fmamk_f32 v139, v139, 0x3e0293ee, v215
	v_fmamk_f32 v140, v140, 0x3e0293ee, v215
	v_fmamk_f32 v141, v141, 0x3e0293ee, v215
	v_fmamk_f32 v142, v142, 0x3e0293ee, v215
	v_exp_f32_e32 v227, v138
	v_fmamk_f32 v130, v130, 0x3e0293ee, v215
	v_fmamk_f32 v138, v155, 0x3e0293ee, v215
	v_exp_f32_e32 v155, v139
	v_fmamk_f32 v139, v156, 0x3e0293ee, v215
	v_exp_f32_e32 v156, v140
	v_fmamk_f32 v140, v157, 0x3e0293ee, v215
	v_exp_f32_e32 v157, v141
	v_fmamk_f32 v141, v158, 0x3e0293ee, v215
	v_exp_f32_e32 v158, v142
	v_fmamk_f32 v142, v159, 0x3e0293ee, v215
	v_fmamk_f32 v146, v146, 0x3e0293ee, v215
	v_exp_f32_e32 v159, v142
	v_fmamk_f32 v142, v143, 0x3e0293ee, v215
	v_exp_f32_e32 v146, v146
	v_fmamk_f32 v147, v147, 0x3e0293ee, v215
	v_exp_f32_e32 v228, v142
	v_fmamk_f32 v142, v160, 0x3e0293ee, v215
	v_exp_f32_e32 v147, v147
	v_fmamk_f32 v148, v148, 0x3e0293ee, v215
	v_exp_f32_e32 v160, v142
	v_fmamk_f32 v142, v144, 0x3e0293ee, v215
	v_exp_f32_e32 v148, v148
	v_fmamk_f32 v149, v149, 0x3e0293ee, v215
	v_exp_f32_e32 v229, v142
	v_fmamk_f32 v142, v161, 0x3e0293ee, v215
	v_exp_f32_e32 v149, v149
	v_fmamk_f32 v150, v150, 0x3e0293ee, v215
	v_exp_f32_e32 v161, v142
	v_fmamk_f32 v142, v145, 0x3e0293ee, v215
	v_exp_f32_e32 v150, v150
	v_fmamk_f32 v151, v151, 0x3e0293ee, v215
	v_exp_f32_e32 v230, v142
	v_add_f32_e32 v142, 0, v146
	v_exp_f32_e32 v151, v151
	v_fmamk_f32 v152, v152, 0x3e0293ee, v215
	v_add_f32_e32 v142, v147, v142
	v_exp_f32_e32 v152, v152
	v_fmamk_f32 v153, v153, 0x3e0293ee, v215
	v_add_f32_e32 v142, v148, v142
	v_exp_f32_e32 v153, v153
	v_fmamk_f32 v154, v154, 0x3e0293ee, v215
	v_add_f32_e32 v142, v149, v142
	v_exp_f32_e32 v154, v154
	v_add_f32_e32 v142, v150, v142
	v_exp_f32_e32 v138, v138
	v_add_f32_e32 v142, v151, v142
	v_exp_f32_e32 v139, v139
	v_add_f32_e32 v142, v152, v142
	v_exp_f32_e32 v140, v140
	v_add_f32_e32 v142, v153, v142
	v_exp_f32_e32 v141, v141
	v_add_f32_e32 v142, v154, v142
	v_add_f32_e32 v142, v138, v142
	v_add_f32_e32 v142, v139, v142
	v_add_f32_e32 v142, v140, v142
	v_exp_f32_e32 v130, v130
	v_fmamk_f32 v131, v131, 0x3e0293ee, v215
	v_add_f32_e32 v142, v141, v142
	v_exp_f32_e32 v131, v131
	v_fmamk_f32 v132, v132, 0x3e0293ee, v215
	v_add_f32_e32 v142, v159, v142
	v_exp_f32_e32 v132, v132
	v_fmamk_f32 v133, v133, 0x3e0293ee, v215
	v_add_f32_e32 v142, v160, v142
	v_exp_f32_e32 v133, v133
	v_fmamk_f32 v134, v134, 0x3e0293ee, v215
	v_add_f32_e32 v142, v161, v142
	v_exp_f32_e32 v134, v134
	v_fmamk_f32 v135, v135, 0x3e0293ee, v215
	v_add_f32_e32 v142, v130, v142
	v_exp_f32_e32 v135, v135
	v_fmamk_f32 v136, v136, 0x3e0293ee, v215
	v_add_f32_e32 v142, v131, v142
	v_exp_f32_e32 v136, v136
	v_fmamk_f32 v137, v137, 0x3e0293ee, v215
	v_add_f32_e32 v142, v132, v142
	v_exp_f32_e32 v137, v137
	v_add_f32_e32 v142, v133, v142
	v_add_f32_e32 v142, v134, v142
	v_add_f32_e32 v142, v135, v142
	v_add_f32_e32 v142, v136, v142
	v_add_f32_e32 v142, v137, v142
	v_add_f32_e32 v142, v227, v142
	v_add_f32_e32 v142, v155, v142
	v_add_f32_e32 v142, v156, v142
	v_add_f32_e32 v142, v157, v142
	v_add_f32_e32 v142, v158, v142
	v_add_f32_e32 v142, v228, v142
	v_add_f32_e32 v142, v229, v142
	v_add_f32_e32 v142, v230, v142
	v_mov_b32_e32 v143, v142
	s_nop 1
	v_permlane32_swap_b32_e32 v142, v143
	v_add_f32_e32 v142, v142, v143
	v_add_f32_e32 v211, v211, v142
	v_cvt_pk_bf16_f32 v142, v146, v147
	v_cvt_pk_bf16_f32 v143, v148, v149
	v_cvt_pk_bf16_f32 v144, v150, v151
	v_cvt_pk_bf16_f32 v145, v152, v153
	s_nop 0
	v_permlane32_swap_b32_e32 v142, v144
	v_permlane32_swap_b32_e32 v143, v145
	v_lshl_add_u32 v146, s4, 15, v217
	v_cvt_pk_bf16_f32 v138, v154, v138
	v_cvt_pk_bf16_f32 v139, v139, v140
	v_cvt_pk_bf16_f32 v140, v141, v159
	v_cvt_pk_bf16_f32 v141, v160, v161
	v_cvt_pk_bf16_f32 v130, v130, v131
	v_cvt_pk_bf16_f32 v131, v132, v133
	v_cvt_pk_bf16_f32 v132, v134, v135
	v_cvt_pk_bf16_f32 v133, v136, v137
	v_cvt_pk_bf16_f32 v134, v227, v155
	v_cvt_pk_bf16_f32 v135, v156, v157
	v_cvt_pk_bf16_f32 v136, v158, v228
	v_cvt_pk_bf16_f32 v137, v229, v230
	v_add_u32_e32 v152, 0xc000, v146
	s_waitcnt vmcnt(0)
	s_barrier
	s_add_i32 s98, s4, -1
	s_cmp_eq_u32 s4, 0
	s_cselect_b32 s98, 2, s98
	s_lshl_b32 s99, s98, 14
	s_add_i32 s99, s90, s99
	s_lshl_b32 s98, s98, 15
	s_add_i32 s98, s90, s98
	v_lshl_add_u64 v[236:237], v[194:195], 0, s[2:3]
	s_mov_b32 m0, s99
	s_nop 0
	global_load_lds_dwordx4 v[236:237], off
	v_lshl_add_u64 v[236:237], v[196:197], 0, s[2:3]
	s_add_i32 m0, s99, 0x2000
	s_nop 0
	global_load_lds_dwordx4 v[236:237], off
	v_lshl_add_u64 v[236:237], v[198:199], 0, s[2:3]
	s_add_i32 m0, s98, 0xc000
	s_nop 0
	global_load_lds_dwordx4 v[236:237], off
	v_lshl_add_u64 v[236:237], v[200:201], 0, s[2:3]
	s_add_i32 m0, s98, 0xe000
	s_nop 0
	global_load_lds_dwordx4 v[236:237], off
	v_lshl_add_u64 v[236:237], v[202:203], 0, s[2:3]
	s_add_i32 m0, s98, 0x10000
	s_nop 0
	global_load_lds_dwordx4 v[236:237], off
	v_lshl_add_u64 v[236:237], v[208:209], 0, s[2:3]
	s_add_i32 m0, s98, 0x12000
	s_nop 0
	global_load_lds_dwordx4 v[236:237], off
	s_cmp_lg_u32 s4, 2
	ds_read_b64_tr_b16 v[148:149], v146 offset:49152
	ds_read_b64_tr_b16 v[150:151], v146 offset:53248
	ds_read_b64_tr_b16 v[154:155], v146 offset:57344
	ds_read_b64_tr_b16 v[156:157], v146 offset:61440
	ds_read_b64_tr_b16 v[158:159], v152 offset:16384
	ds_read_b64_tr_b16 v[160:161], v152 offset:20480
	ds_read_b64_tr_b16 v[232:233], v152 offset:24576
	ds_read_b64_tr_b16 v[234:235], v152 offset:28672
	ds_read_b64_tr_b16 v[236:237], v146 offset:49664
	ds_read_b64_tr_b16 v[238:239], v146 offset:53760
	ds_read_b64_tr_b16 v[240:241], v146 offset:57856
	ds_read_b64_tr_b16 v[242:243], v146 offset:61952
	s_setprio 1
	s_waitcnt lgkmcnt(8)
	ds_read_b64_tr_b16 v[246:247], v152 offset:16896
	ds_read_b64_tr_b16 v[248:249], v152 offset:20992
	ds_read_b64_tr_b16 v[250:251], v152 offset:25088
	ds_read_b64_tr_b16 v[252:253], v152 offset:29184
	v_mfma_f32_32x32x16_bf16 v[114:129], v[142:145], v[148:151], v[114:129]
	v_permlane32_swap_b32_e32 v138, v140
	v_permlane32_swap_b32_e32 v139, v141
	v_permlane32_swap_b32_e32 v130, v132
	v_permlane32_swap_b32_e32 v131, v133
	v_mfma_f32_32x32x16_bf16 v[114:129], v[138:141], v[154:157], v[114:129]
	v_permlane32_swap_b32_e32 v134, v136
	v_permlane32_swap_b32_e32 v135, v137
	s_cselect_b32 s4, s5, 0
	s_add_u32 s2, s2, 0x100000
	s_addc_u32 s3, s3, 0
	s_waitcnt lgkmcnt(8)
	ds_read_b64_tr_b16 v[148:149], v146 offset:50176
	ds_read_b64_tr_b16 v[150:151], v146 offset:54272
	ds_read_b64_tr_b16 v[154:155], v146 offset:58368
	ds_read_b64_tr_b16 v[156:157], v146 offset:62464
	v_mfma_f32_32x32x16_bf16 v[114:129], v[130:133], v[158:161], v[114:129]
	v_mfma_f32_32x32x16_bf16 v[114:129], v[134:137], v[232:235], v[114:129]
	s_cmp_eq_u32 s2, 0x2200000
	s_waitcnt lgkmcnt(8)
	ds_read_b64_tr_b16 v[158:159], v152 offset:17408
	ds_read_b64_tr_b16 v[160:161], v152 offset:21504
	ds_read_b64_tr_b16 v[232:233], v152 offset:25600
	ds_read_b64_tr_b16 v[234:235], v152 offset:29696
	v_mfma_f32_32x32x16_bf16 v[98:113], v[142:145], v[236:239], v[98:113]
	v_mfma_f32_32x32x16_bf16 v[98:113], v[138:141], v[240:243], v[98:113]
	s_waitcnt lgkmcnt(8)
	ds_read_b64_tr_b16 v[236:237], v146 offset:50688
	ds_read_b64_tr_b16 v[238:239], v146 offset:54784
	ds_read_b64_tr_b16 v[240:241], v146 offset:58880
	ds_read_b64_tr_b16 v[242:243], v146 offset:62976
	v_mfma_f32_32x32x16_bf16 v[98:113], v[130:133], v[246:249], v[98:113]
	v_mfma_f32_32x32x16_bf16 v[98:113], v[134:137], v[250:253], v[98:113]
	s_waitcnt lgkmcnt(8)
	ds_read_b64_tr_b16 v[246:247], v152 offset:17920
	ds_read_b64_tr_b16 v[248:249], v152 offset:22016
	ds_read_b64_tr_b16 v[250:251], v152 offset:26112
	ds_read_b64_tr_b16 v[252:253], v152 offset:30208
	v_mfma_f32_32x32x16_bf16 v[82:97], v[142:145], v[148:151], v[82:97]
	v_mfma_f32_32x32x16_bf16 v[82:97], v[138:141], v[154:157], v[82:97]
	s_waitcnt lgkmcnt(8)
	ds_read_b64_tr_b16 v[148:149], v146 offset:51200
	ds_read_b64_tr_b16 v[150:151], v146 offset:55296
	ds_read_b64_tr_b16 v[154:155], v146 offset:59392
	ds_read_b64_tr_b16 v[156:157], v146 offset:63488
	v_mfma_f32_32x32x16_bf16 v[82:97], v[130:133], v[158:161], v[82:97]
	v_mfma_f32_32x32x16_bf16 v[82:97], v[134:137], v[232:235], v[82:97]
	s_waitcnt lgkmcnt(8)
	ds_read_b64_tr_b16 v[158:159], v152 offset:18432
	ds_read_b64_tr_b16 v[160:161], v152 offset:22528
	ds_read_b64_tr_b16 v[232:233], v152 offset:26624
	ds_read_b64_tr_b16 v[234:235], v152 offset:30720
	v_mfma_f32_32x32x16_bf16 v[66:81], v[142:145], v[236:239], v[66:81]
	v_mfma_f32_32x32x16_bf16 v[66:81], v[138:141], v[240:243], v[66:81]
	s_waitcnt lgkmcnt(8)
	ds_read_b64_tr_b16 v[236:237], v146 offset:51712
	ds_read_b64_tr_b16 v[238:239], v146 offset:55808
	ds_read_b64_tr_b16 v[240:241], v146 offset:59904
	ds_read_b64_tr_b16 v[242:243], v146 offset:64000
	v_mfma_f32_32x32x16_bf16 v[66:81], v[130:133], v[246:249], v[66:81]
	v_mfma_f32_32x32x16_bf16 v[66:81], v[134:137], v[250:253], v[66:81]
	s_waitcnt lgkmcnt(8)
	ds_read_b64_tr_b16 v[246:247], v152 offset:18944
	ds_read_b64_tr_b16 v[248:249], v152 offset:23040
	ds_read_b64_tr_b16 v[250:251], v152 offset:27136
	ds_read_b64_tr_b16 v[252:253], v152 offset:31232
	v_mfma_f32_32x32x16_bf16 v[50:65], v[142:145], v[148:151], v[50:65]
	v_mfma_f32_32x32x16_bf16 v[50:65], v[138:141], v[154:157], v[50:65]
	s_waitcnt lgkmcnt(8)
	ds_read_b64_tr_b16 v[148:149], v146 offset:52224
	ds_read_b64_tr_b16 v[150:151], v146 offset:56320
	ds_read_b64_tr_b16 v[154:155], v146 offset:60416
	ds_read_b64_tr_b16 v[156:157], v146 offset:64512
	v_mfma_f32_32x32x16_bf16 v[50:65], v[130:133], v[158:161], v[50:65]
	v_mfma_f32_32x32x16_bf16 v[50:65], v[134:137], v[232:235], v[50:65]
	s_waitcnt lgkmcnt(8)
	ds_read_b64_tr_b16 v[158:159], v152 offset:19456
	ds_read_b64_tr_b16 v[160:161], v152 offset:23552
	ds_read_b64_tr_b16 v[232:233], v152 offset:27648
	ds_read_b64_tr_b16 v[234:235], v152 offset:31744
	v_mfma_f32_32x32x16_bf16 v[34:49], v[142:145], v[236:239], v[34:49]
	v_mfma_f32_32x32x16_bf16 v[34:49], v[138:141], v[240:243], v[34:49]
	s_waitcnt lgkmcnt(8)
	ds_read_b64_tr_b16 v[236:237], v146 offset:52736
	ds_read_b64_tr_b16 v[238:239], v146 offset:56832
	ds_read_b64_tr_b16 v[240:241], v146 offset:60928
	ds_read_b64_tr_b16 v[242:243], v146 offset:65024
	v_mfma_f32_32x32x16_bf16 v[34:49], v[130:133], v[246:249], v[34:49]
	v_mfma_f32_32x32x16_bf16 v[34:49], v[134:137], v[250:253], v[34:49]
	s_waitcnt lgkmcnt(8)
	ds_read_b64_tr_b16 v[246:247], v152 offset:19968
	ds_read_b64_tr_b16 v[248:249], v152 offset:24064
	ds_read_b64_tr_b16 v[250:251], v152 offset:28160
	ds_read_b64_tr_b16 v[252:253], v152 offset:32256
	v_mfma_f32_32x32x16_bf16 v[18:33], v[142:145], v[148:151], v[18:33]
	v_mfma_f32_32x32x16_bf16 v[18:33], v[138:141], v[154:157], v[18:33]
	s_waitcnt lgkmcnt(8)
	v_mfma_f32_32x32x16_bf16 v[18:33], v[130:133], v[158:161], v[18:33]
	v_mfma_f32_32x32x16_bf16 v[18:33], v[134:137], v[232:235], v[18:33]
	s_waitcnt lgkmcnt(4)
	v_mfma_f32_32x32x16_bf16 v[2:17], v[142:145], v[236:239], v[2:17]
	v_mfma_f32_32x32x16_bf16 v[2:17], v[138:141], v[240:243], v[2:17]
	s_waitcnt lgkmcnt(0)
	v_mfma_f32_32x32x16_bf16 v[2:17], v[130:133], v[246:249], v[2:17]
	v_mfma_f32_32x32x16_bf16 v[2:17], v[134:137], v[250:253], v[2:17]
	s_setprio 0
	s_cbranch_scc0 .LBB0_1256
	s_cmp_ge_u32 s66, 0x80
	s_cbranch_scc1 .Lst2_b
	s_barrier

	.amdhsa_kernel _Z10fwd_kernel6Params
		.amdhsa_group_segment_fixed_size 0
		.amdhsa_private_segment_fixed_size 0
		.amdhsa_kernarg_size 464
		.amdhsa_user_sgpr_count 2
		.amdhsa_user_sgpr_dispatch_ptr 0
		.amdhsa_user_sgpr_queue_ptr 0
		.amdhsa_user_sgpr_kernarg_segment_ptr 1
		.amdhsa_user_sgpr_dispatch_id 0
		.amdhsa_user_sgpr_kernarg_preload_length 0
		.amdhsa_user_sgpr_kernarg_preload_offset 0
		.amdhsa_user_sgpr_private_segment_size 0
		.amdhsa_uses_dynamic_stack 0
		.amdhsa_enable_private_segment 0
		.amdhsa_system_sgpr_workgroup_id_x 1
		.amdhsa_system_sgpr_workgroup_id_y 0
		.amdhsa_system_sgpr_workgroup_id_z 0
		.amdhsa_system_sgpr_workgroup_info 0
		.amdhsa_system_vgpr_workitem_id 2
		.amdhsa_next_free_vgpr 256
		.amdhsa_next_free_sgpr 102
		.amdhsa_accum_offset 256
		.amdhsa_reserve_vcc 1
		.amdhsa_float_round_mode_32 0
		.amdhsa_float_round_mode_16_64 0
		.amdhsa_float_denorm_mode_32 3
		.amdhsa_float_denorm_mode_16_64 3
		.amdhsa_dx10_clamp 1
		.amdhsa_ieee_mode 1
		.amdhsa_fp16_overflow 0
		.amdhsa_tg_split 0
		.amdhsa_exception_fp_ieee_invalid_op 0
		.amdhsa_exception_fp_denorm_src 0
		.amdhsa_exception_fp_ieee_div_zero 0
		.amdhsa_exception_fp_ieee_overflow 0
		.amdhsa_exception_fp_ieee_underflow 0
		.amdhsa_exception_fp_ieee_inexact 0
		.amdhsa_exception_int_div_zero 0
	.end_amdhsa_kernel

amdhsa.kernels:
  - .agpr_count:     0
    .args:
      - .offset:         0
        .size:           208
        .value_kind:     by_value
      - .offset:         208
        .size:           4
        .value_kind:     hidden_block_count_x
      - .offset:         212
        .size:           4
        .value_kind:     hidden_block_count_y
      - .offset:         216
        .size:           4
        .value_kind:     hidden_block_count_z
      - .offset:         220
        .size:           2
        .value_kind:     hidden_group_size_x
      - .offset:         222
        .size:           2
        .value_kind:     hidden_group_size_y
      - .offset:         224
        .size:           2
        .value_kind:     hidden_group_size_z
      - .offset:         226
        .size:           2
        .value_kind:     hidden_remainder_x
      - .offset:         228
        .size:           2
        .value_kind:     hidden_remainder_y
      - .offset:         230
        .size:           2
        .value_kind:     hidden_remainder_z
      - .offset:         248
        .size:           8
        .value_kind:     hidden_global_offset_x
      - .offset:         256
        .size:           8
        .value_kind:     hidden_global_offset_y
      - .offset:         264
        .size:           8
        .value_kind:     hidden_global_offset_z
      - .offset:         272
        .size:           2
        .value_kind:     hidden_grid_dims
      - .offset:         296
        .size:           8
        .value_kind:     hidden_multigrid_sync_arg
      - .offset:         328
        .size:           4
        .value_kind:     hidden_dynamic_lds_size
    .group_segment_fixed_size: 0
    .kernarg_segment_align: 8
    .kernarg_segment_size: 464
    .language:       OpenCL C
    .language_version:
      - 2
      - 0
    .max_flat_workgroup_size: 512
    .name:           _Z10fwd_kernel6Params
    .private_segment_fixed_size: 0
    .sgpr_count:     108
    .sgpr_spill_count: 137
    .symbol:         _Z10fwd_kernel6Params.kd
    .uniform_work_group_size: 1
    .uses_dynamic_stack: false
    .vgpr_count:     256
    .vgpr_spill_count: 0
    .wavefront_size: 64
